# phase-0 silu(c) prologue: all eight conditioning loads in flight before the evaluations (on top of dense rewrite)
# baseline (speedup 1.0000x reference)
; __device__ __forceinline__ const float* INP(int i) { const CAS char* k = (const CAS char*)__builtin_amdgcn_kernarg_segment_ptr(); asm volatile("" : "+s"(k)); return *(const float* const CAS*)(k + 8 * i); }
; __device__ __forceinline__ void phase0(const Args& a, unsigned char* lds_g, int G) {
;     ...
;     for (int i = tid; i < DM; i += 512) { const float c = INP(I_C)[i]; sc[i] = c / (1.0f + __expf(-c)); const float cc = INP(I_CCTX)[i]; sc[DM + i] = cc / (1.0f + __expf(-cc)); }
.LBB0_89:
	v_mov_b32_e32 v8, v216
	s_movk_i32 s2, 0x800
	s_mov_b32 s12, s80
	v_cmp_gt_i32_e32 vcc, s2, v8
	s_and_saveexec_b64 s[6:7], vcc
	s_cbranch_execz .LBB0_92
	s_load_dwordx2 s[10:11], s[0:1], 0x8
	s_load_dwordx2 s[14:15], s[0:1], 0x18
	v_lshlrev_b32_e32 v0, 2, v8
	v_add_u32_e32 v1, 0x1000, v0
	v_lshl_add_u32 v3, v8, 2, 0
	s_waitcnt lgkmcnt(0)
	global_load_dword v20, v0, s[10:11]
	global_load_dword v21, v0, s[10:11] offset:2048
	global_load_dword v22, v1, s[10:11]
	global_load_dword v23, v1, s[10:11] offset:2048
	global_load_dword v24, v0, s[14:15]
	global_load_dword v25, v0, s[14:15] offset:2048
	global_load_dword v26, v1, s[14:15]
	global_load_dword v27, v1, s[14:15] offset:2048
	s_waitcnt vmcnt(0)
	v_mul_f32_e32 v5, 0xbfb8aa3b, v20
	v_exp_f32_e32 v5, v5
	s_nop 0
	v_add_f32_e32 v5, 1.0, v5
	v_div_scale_f32 v6, s[10:11], v5, v5, v20
	v_rcp_f32_e32 v9, v6
	v_div_scale_f32 v7, vcc, v20, v5, v20
	v_fma_f32 v10, -v6, v9, 1.0
	v_fmac_f32_e32 v9, v10, v9
	v_mul_f32_e32 v10, v7, v9
	v_fma_f32 v11, -v6, v10, v7
	v_fmac_f32_e32 v10, v11, v9
	v_fma_f32 v6, -v6, v10, v7
	v_div_fmas_f32 v6, v6, v9, v10
	v_div_fixup_f32 v4, v6, v5, v20
	ds_write_b32 v3, v4
	v_mul_f32_e32 v5, 0xbfb8aa3b, v21
	v_exp_f32_e32 v5, v5
	s_nop 0
	v_add_f32_e32 v5, 1.0, v5
	v_div_scale_f32 v6, s[10:11], v5, v5, v21
	v_rcp_f32_e32 v9, v6
	v_div_scale_f32 v7, vcc, v21, v5, v21
	v_fma_f32 v10, -v6, v9, 1.0
	v_fmac_f32_e32 v9, v10, v9
	v_mul_f32_e32 v10, v7, v9
	v_fma_f32 v11, -v6, v10, v7
	v_fmac_f32_e32 v10, v11, v9
	v_fma_f32 v6, -v6, v10, v7
	v_div_fmas_f32 v6, v6, v9, v10
	v_div_fixup_f32 v4, v6, v5, v21
	ds_write_b32 v3, v4 offset:2048
	v_mul_f32_e32 v5, 0xbfb8aa3b, v22
	v_exp_f32_e32 v5, v5
	s_nop 0
	v_add_f32_e32 v5, 1.0, v5
	v_div_scale_f32 v6, s[10:11], v5, v5, v22
	v_rcp_f32_e32 v9, v6
	v_div_scale_f32 v7, vcc, v22, v5, v22
	v_fma_f32 v10, -v6, v9, 1.0
	v_fmac_f32_e32 v9, v10, v9
	v_mul_f32_e32 v10, v7, v9
	v_fma_f32 v11, -v6, v10, v7
	v_fmac_f32_e32 v10, v11, v9
	v_fma_f32 v6, -v6, v10, v7
	v_div_fmas_f32 v6, v6, v9, v10
	v_div_fixup_f32 v4, v6, v5, v22
	ds_write_b32 v3, v4 offset:4096
	v_mul_f32_e32 v5, 0xbfb8aa3b, v23
	v_exp_f32_e32 v5, v5
	s_nop 0
	v_add_f32_e32 v5, 1.0, v5
	v_div_scale_f32 v6, s[10:11], v5, v5, v23
	v_rcp_f32_e32 v9, v6
	v_div_scale_f32 v7, vcc, v23, v5, v23
	v_fma_f32 v10, -v6, v9, 1.0
	v_fmac_f32_e32 v9, v10, v9
	v_mul_f32_e32 v10, v7, v9
	v_fma_f32 v11, -v6, v10, v7
	v_fmac_f32_e32 v10, v11, v9
	v_fma_f32 v6, -v6, v10, v7
	v_div_fmas_f32 v6, v6, v9, v10
	v_div_fixup_f32 v4, v6, v5, v23
	ds_write_b32 v3, v4 offset:6144
	v_mul_f32_e32 v5, 0xbfb8aa3b, v24
	v_exp_f32_e32 v5, v5
	s_nop 0
	v_add_f32_e32 v5, 1.0, v5
	v_div_scale_f32 v6, s[10:11], v5, v5, v24
	v_rcp_f32_e32 v9, v6
	v_div_scale_f32 v7, vcc, v24, v5, v24
	v_fma_f32 v10, -v6, v9, 1.0
	v_fmac_f32_e32 v9, v10, v9
	v_mul_f32_e32 v10, v7, v9
	v_fma_f32 v11, -v6, v10, v7
	v_fmac_f32_e32 v10, v11, v9
	v_fma_f32 v6, -v6, v10, v7
	v_div_fmas_f32 v6, v6, v9, v10
	v_div_fixup_f32 v4, v6, v5, v24
	ds_write_b32 v3, v4 offset:8192
	v_mul_f32_e32 v5, 0xbfb8aa3b, v25
	v_exp_f32_e32 v5, v5
	s_nop 0
	v_add_f32_e32 v5, 1.0, v5
	v_div_scale_f32 v6, s[10:11], v5, v5, v25
	v_rcp_f32_e32 v9, v6
	v_div_scale_f32 v7, vcc, v25, v5, v25
	v_fma_f32 v10, -v6, v9, 1.0
	v_fmac_f32_e32 v9, v10, v9
	v_mul_f32_e32 v10, v7, v9
	v_fma_f32 v11, -v6, v10, v7
	v_fmac_f32_e32 v10, v11, v9
	v_fma_f32 v6, -v6, v10, v7
	v_div_fmas_f32 v6, v6, v9, v10
	v_div_fixup_f32 v4, v6, v5, v25
	ds_write_b32 v3, v4 offset:10240
	v_mul_f32_e32 v5, 0xbfb8aa3b, v26
	v_exp_f32_e32 v5, v5
	s_nop 0
	v_add_f32_e32 v5, 1.0, v5
	v_div_scale_f32 v6, s[10:11], v5, v5, v26
	v_rcp_f32_e32 v9, v6
	v_div_scale_f32 v7, vcc, v26, v5, v26
	v_fma_f32 v10, -v6, v9, 1.0
	v_fmac_f32_e32 v9, v10, v9
	v_mul_f32_e32 v10, v7, v9
	v_fma_f32 v11, -v6, v10, v7
	v_fmac_f32_e32 v10, v11, v9
	v_fma_f32 v6, -v6, v10, v7
	v_div_fmas_f32 v6, v6, v9, v10
	v_div_fixup_f32 v4, v6, v5, v26
	ds_write_b32 v3, v4 offset:12288
	v_mul_f32_e32 v5, 0xbfb8aa3b, v27
	v_exp_f32_e32 v5, v5
	s_nop 0
	v_add_f32_e32 v5, 1.0, v5
	v_div_scale_f32 v6, s[10:11], v5, v5, v27
	v_rcp_f32_e32 v9, v6
	v_div_scale_f32 v7, vcc, v27, v5, v27
	v_fma_f32 v10, -v6, v9, 1.0
	v_fmac_f32_e32 v9, v10, v9
	v_mul_f32_e32 v10, v7, v9
	v_fma_f32 v11, -v6, v10, v7
	v_fmac_f32_e32 v10, v11, v9
	v_fma_f32 v6, -v6, v10, v7
	v_div_fmas_f32 v6, v6, v9, v10
	v_div_fixup_f32 v4, v6, v5, v27
	ds_write_b32 v3, v4 offset:14336
